# hand-written weight-transpose loop in phase 0 (8 dwordx4 loads in flight per tile) on top of v30
# speedup vs baseline: 1.0000x; 1.0000x over previous
; #define LAS __attribute__((address_space(3)))
; __device__ __forceinline__ int srccol(int map, int rb) {
;     const int r = rb * 32;
;     switch (map) {
;         case 1: { const int pn = r >> 8, w = r & 255; return w < 128 ? 128 * pn + w : DFF + 128 * pn + (w - 128); }
;         case 2: { if (r < 416) return r; if (r < 512) return -1; return r - 96; }
;         case 3: return 2464 + r;
;         case 4: { const int v = r >= 512 ? 1 : 0; const int rr = r & 511; return (rr >> 6) * 128 + (rr & 63) + 64 * v; }
;         default: return r;
;     }
; }
; __device__ __forceinline__ TJob get_job(const Params& p, int j) {
;     TJob t; t.scale = nullptr; t.dstk0 = 0; t.map = 0; t.nbatch = 1; t.sbs = 0; t.dbs = 0;
;     unsigned char* ws = p.ws;
;     switch (j) {
;         case 0:  t.src = p.in[8];  t.dst = (bf16_t*)(ws + WS_WGU1); t.ldsrc = 2 * DFF; t.K = D; t.lddst = D; t.nrb = 176; t.map = 1; break;
; __device__ __forceinline__ void phase_prep(const Params& p, LAS unsigned char* lds) {
;     const int tid = threadIdx.x, lane = tid & 63, wave = tid >> 6;
;     const int gw = blockIdx.x * NWAVES + wave, NGW = gridDim.x * NWAVES;
;     {
;         LAS float* scr = (LAS float*)(lds + wave * 8704);
;         int base = 0;
;         for (int j = 0; j < NJOBS; ++j) {
;             const TJob jb = get_job(p, j); const int n = job_items(jb);
;             int first = gw - (base % NGW); if (first < 0) first += NGW;
;             for (int i = first; i < n; i += NGW) tr_item(jb, i, scr, lane);
;             base += n;
;         }
.LBB0_25:
	s_load_dwordx16 s[8:23], s[0:1], 0x0
	s_load_dwordx16 s[36:51], s[0:1], 0x40
	s_andn2_b64 vcc, exec, s[6:7]
	v_lshrrev_b32_e32 v129, 6, v128
	s_waitcnt lgkmcnt(0)
	v_writelane_b32 v249, s36, 10
	s_nop 1
	v_writelane_b32 v249, s37, 11
	v_writelane_b32 v249, s38, 12
	v_writelane_b32 v249, s39, 13
	v_writelane_b32 v249, s40, 14
	v_writelane_b32 v249, s41, 15
	v_writelane_b32 v249, s42, 16
	v_writelane_b32 v249, s43, 17
	v_writelane_b32 v249, s44, 18
	v_writelane_b32 v249, s45, 19
	v_writelane_b32 v249, s46, 20
	v_writelane_b32 v249, s47, 21
	v_writelane_b32 v249, s48, 22
	v_writelane_b32 v249, s49, 23
	v_writelane_b32 v249, s50, 24
	v_writelane_b32 v249, s51, 25
	s_load_dwordx16 s[36:51], s[0:1], 0x80
	s_cbranch_vccnz .LBB0_146
	v_writelane_b32 v249, s30, 26
	s_lshl_b32 s3, s90, 3
	s_movk_i32 s0, 0x2200
	v_writelane_b32 v249, s31, 27
	v_writelane_b32 v249, s64, 28
	v_mad_u32_u24 v3, v129, s0, 0
	s_add_u32 s0, s92, 0x3080000
	v_writelane_b32 v249, s65, 29
	v_writelane_b32 v249, s96, 30
	s_addc_u32 s1, s93, 0
	v_lshlrev_b32_e32 v6, 3, v128
	v_writelane_b32 v249, s97, 31
	v_writelane_b32 v249, s0, 32
	v_and_b32_e32 v10, 56, v6
	v_and_b32_e32 v0, 31, v128
	v_writelane_b32 v249, s1, 33
	s_add_u32 s0, s92, 0x2b00000
	s_addc_u32 s1, s93, 0
	v_writelane_b32 v249, s0, 34
	v_bfe_u32 v18, v128, 3, 3
	v_lshlrev_b32_e32 v8, 2, v0
	v_writelane_b32 v249, s1, 35
	s_add_u32 s0, s92, 0x2000000
	s_addc_u32 s1, s93, 0
	v_writelane_b32 v249, s0, 36
	v_mul_u32_u24_e32 v7, 0x84, v10
	v_lshlrev_b32_e32 v9, 2, v18
	v_writelane_b32 v249, s1, 37
	s_add_u32 s0, s92, 0x1e00000
	s_addc_u32 s1, s93, 0
	v_writelane_b32 v249, s0, 38
	v_add_u32_e32 v4, v3, v8
	v_add3_u32 v19, v3, v7, v9
	v_writelane_b32 v249, s1, 39
	s_add_u32 s0, s92, 0x1c00000
	s_addc_u32 s1, s93, 0
	v_writelane_b32 v249, s0, 40
	v_bfe_u32 v2, v128, 5, 1
	v_mul_u32_u24_e32 v5, 0x2200, v129
	v_writelane_b32 v249, s1, 41
	s_add_u32 s0, s92, 0x1b00000
	s_addc_u32 s1, s93, 0
	v_writelane_b32 v249, s0, 42
	v_mul_u32_u24_e32 v9, 0x84, v2
	s_mov_b32 s35, 0
	v_writelane_b32 v249, s1, 43
	s_add_u32 s0, s92, 0x1a10000
	s_addc_u32 s1, s93, 0
	v_writelane_b32 v249, s0, 44
	v_mov_b32_e32 v1, 0
	v_or_b32_e32 v5, v5, v9
	v_writelane_b32 v249, s1, 45
	s_add_u32 s0, s92, 0x1980000
	s_addc_u32 s1, s93, 0
	v_writelane_b32 v249, s0, 46
	v_and_b32_e32 v36, 63, v128
	v_lshl_add_u32 v11, s2, 3, v129
	v_writelane_b32 v249, s1, 47
	s_add_u32 s0, s92, 0x1580000
	s_addc_u32 s1, s93, 0
	v_writelane_b32 v249, s0, 48
	v_or_b32_e32 v20, 8, v18
	v_or_b32_e32 v21, 16, v18
	v_writelane_b32 v249, s1, 49
	s_add_u32 s0, s92, 0x1080000
	s_addc_u32 s1, s93, 0
	v_writelane_b32 v249, s0, 50
	v_or_b32_e32 v22, 24, v18
	v_mov_b32_e32 v7, v1
	v_writelane_b32 v249, s1, 51
	s_add_u32 s0, s92, 0xb00000
	s_addc_u32 s1, s93, 0
	v_writelane_b32 v249, s0, 52
	s_add_u32 s64, s92, 0x3088000
	v_add3_u32 v23, v5, v8, 0
	v_writelane_b32 v249, s1, 53
	v_writelane_b32 v249, s92, 54
	s_addc_u32 s65, s93, 0
	s_abs_i32 s33, s3
	v_cvt_f32_u32_e32 v6, s33
	v_writelane_b32 v249, s93, 55
	s_sub_i32 s0, 0, s33
	v_writelane_b32 v249, s94, 56
	v_rcp_iflag_f32_e32 v6, v6
	v_writelane_b32 v249, s95, 57
	s_movk_i32 s94, 0x84
	v_writelane_b32 v249, s90, 58
	v_mul_f32_e32 v3, 0x4f7ffffe, v6
	v_cvt_u32_f32_e32 v6, v3
	v_mov_b32_e32 v3, v2
	s_lshl_b32 s96, s90, 9
	v_lshlrev_b32_e32 v8, 2, v0
	v_readfirstlane_b32 s1, v6
	s_mul_i32 s0, s0, s1
	s_mul_hi_u32 s0, s1, s0
	s_add_i32 s95, s1, s0
	v_mov_b32_e32 v6, v2
	v_lshlrev_b32_e32 v0, 1, v10
	s_mov_b32 s97, 0
	s_mov_b32 s34, s35
	v_writelane_b32 v249, s91, 59
	s_waitcnt lgkmcnt(0)
	v_readfirstlane_b32 s82, v129
	v_mbcnt_lo_u32_b32 v240, -1, 0
	v_mbcnt_hi_u32_b32 v240, -1, v240
	v_and_b32_e32 v241, 7, v240
	v_lshrrev_b32_e32 v240, 3, v240
	v_mul_u32_u24_e32 v245, 0x420, v241
	v_lshlrev_b32_e32 v241, 4, v241
	v_lshlrev_b32_e32 v246, 2, v240
	s_mul_i32 s74, s82, 0x2200
	s_movk_i32 s75, 0x84
	v_mad_u32_u24 v244, v240, s75, v241
	v_add_u32_e32 v245, v245, v246
	v_add_u32_e32 v244, s74, v244
	v_add_u32_e32 v245, s74, v245
	s_lshl_b32 s52, s2, 3
	s_add_u32 s52, s52, s82
	s_lshl_b32 s53, s90, 3
.Lprep_item:
	s_cmp_ge_u32 s52, 12624
	s_cbranch_scc1 .Lprep_done
	s_cmp_lt_u32 s52, 2816
	s_cbranch_scc1 .Lprep_j0
	s_cmp_lt_u32 s52, 4224
	s_cbranch_scc1 .Lprep_j1
	s_cmp_lt_u32 s52, 5504
	s_cbranch_scc1 .Lprep_j2
	s_cmp_lt_u32 s52, 6528
	s_cbranch_scc1 .Lprep_j3
	s_cmp_lt_u32 s52, 6624
	s_cbranch_scc1 .Lprep_j4
	s_cmp_lt_u32 s52, 6672
	s_cbranch_scc1 .Lprep_j5
	s_cmp_lt_u32 s52, 6736
	s_cbranch_scc1 .Lprep_j6
	s_cmp_lt_u32 s52, 6864
	s_cbranch_scc1 .Lprep_j7
	s_cmp_lt_u32 s52, 7120
	s_cbranch_scc1 .Lprep_j8
	s_cmp_lt_u32 s52, 7632
	s_cbranch_scc1 .Lprep_j9
	s_cmp_lt_u32 s52, 8144
	s_cbranch_scc1 .Lprep_j10
	s_cmp_lt_u32 s52, 10960
	s_cbranch_scc1 .Lprep_j11
	s_cmp_lt_u32 s52, 12368
	s_cbranch_scc1 .Lprep_j12
	s_cmp_lt_u32 s52, 12496
	s_cbranch_scc1 .Lprep_j13
	s_branch .Lprep_j14
.Lprep_j0:
	s_mov_b32 s54, s52
	s_lshr_b32 s63, s54, 8
	s_lshl_b32 s63, s63, 4
	s_and_b32 s74, s54, 15
	s_or_b32 s63, s63, s74
	s_bfe_u32 s73, s54, 0x40004
	s_lshl_b32 s62, s73, 6
	s_add_u32 s68, s92, 0x0
	s_addc_u32 s69, s93, 0
	s_movk_i32 s70, 0x800
	s_mov_b32 s71, s62
	s_lshr_b32 s61, s63, 3
	s_lshl_b32 s61, s61, 7
	s_and_b32 s74, s63, 7
	s_lshl_b32 s74, s74, 5
	s_add_u32 s61, s61, s74
	s_and_b32 s74, s63, 4
	s_cmp_lg_u32 s74, 0
	s_cselect_b32 s74, 0xa80, 0
	s_add_u32 s61, s61, s74
	v_readlane_b32 s56, v249, 10
	v_readlane_b32 s57, v249, 11
	s_mov_b64 s[66:67], 0
	s_nop 4
	s_movk_i32 s60, 0x5800
	s_branch .Lprep_tile
; __device__ __forceinline__ int srccol(int map, int rb) {
;     const int r = rb * 32;
;     switch (map) {
;         case 1: { const int pn = r >> 8, w = r & 255; return w < 128 ? 128 * pn + w : DFF + 128 * pn + (w - 128); }
;         case 2: { if (r < 416) return r; if (r < 512) return -1; return r - 96; }
;         case 3: return 2464 + r;
;         case 4: { const int v = r >= 512 ? 1 : 0; const int rr = r & 511; return (rr >> 6) * 128 + (rr & 63) + 64 * v; }
;         default: return r;
;     }
; }
; __device__ __forceinline__ TJob get_job(const Params& p, int j) {
;     TJob t; t.scale = nullptr; t.dstk0 = 0; t.map = 0; t.nbatch = 1; t.sbs = 0; t.dbs = 0;
;     unsigned char* ws = p.ws;
;     switch (j) {
;         case 0:  t.src = p.in[8];  t.dst = (bf16_t*)(ws + WS_WGU1); t.ldsrc = 2 * DFF; t.K = D; t.lddst = D; t.nrb = 176; t.map = 1; break;
;         case 1:  t.src = p.in[9];  t.dst = (bf16_t*)(ws + WS_WDN1); t.ldsrc = D; t.K = DFF; t.lddst = DFF; t.nrb = 32; break;
;         case 2:  t.src = p.in[10]; t.dst = (bf16_t*)(ws + WS_WINA); t.ldsrc = 4512; t.K = D; t.lddst = D; t.nrb = 80; t.map = 2; break;
;         case 3:  t.src = p.in[10]; t.dst = (bf16_t*)(ws + WS_WINB); t.ldsrc = 4512; t.K = D; t.lddst = D; t.nrb = 64; t.map = 3; break;
;         case 4:  t.src = p.in[13]; t.scale = p.in[11]; t.dst = (bf16_t*)(ws + WS_WQKV); t.ldsrc = 768; t.K = 256; t.lddst = 384; t.nrb = 24; break;
;         case 5:  t.src = nullptr;  t.dst = (bf16_t*)(ws + WS_WQKV); t.ldsrc = 0; t.K = 128; t.lddst = 384; t.dstk0 = 256; t.nrb = 24; break;
;         case 6:  t.src = p.in[14]; t.scale = p.in[12]; t.dst = (bf16_t*)(ws + WS_WQKV) + 768 * 384; t.ldsrc = 1024; t.K = 128; t.lddst = 384; t.dstk0 = 256; t.nrb = 32; t.map = 4; break;
;         case 7:  t.src = nullptr;  t.dst = (bf16_t*)(ws + WS_WQKV) + 768 * 384; t.ldsrc = 0; t.K = 256; t.lddst = 384; t.nrb = 32; break;
;         case 8:  t.src = p.in[15]; t.dst = (bf16_t*)(ws + WS_WAO); t.ldsrc = D; t.K = 512; t.lddst = 512; t.nrb = 32; break;
;         case 9:  t.src = p.in[23]; t.dst = (bf16_t*)(ws + WS_WLO); t.ldsrc = D; t.K = D; t.lddst = D; t.nrb = 32; break;
;         case 10: t.src = p.in[24]; t.dst = (bf16_t*)(ws + WS_WOUT); t.ldsrc = D; t.K = D; t.lddst = D; t.nrb = 32; break;
.Lprep_j1:
	s_sub_u32 s54, s52, 2816
	s_and_b32 s63, s54, 31
	s_lshr_b32 s73, s54, 5
	s_lshl_b32 s62, s73, 6
	s_add_u32 s68, s92, 0xb00000
	s_addc_u32 s69, s93, 0
	s_movk_i32 s70, 0x1600
	s_mov_b32 s71, s62
	s_lshl_b32 s61, s63, 5
	v_readlane_b32 s56, v249, 12
	v_readlane_b32 s57, v249, 13
	s_mov_b64 s[66:67], 0
	s_nop 4
	s_movk_i32 s60, 0x1000
	s_branch .Lprep_tile
.Lprep_j2:
	s_sub_u32 s54, s52, 4224
	s_lshr_b32 s63, s54, 8
	s_lshl_b32 s63, s63, 4
	s_and_b32 s74, s54, 15
	s_or_b32 s63, s63, s74
	s_bfe_u32 s73, s54, 0x40004
	s_lshl_b32 s62, s73, 6
	s_add_u32 s68, s92, 0x1080000
	s_addc_u32 s69, s93, 0
	s_movk_i32 s70, 0x800
	s_mov_b32 s71, s62
	s_lshl_b32 s61, s63, 5
	s_cmp_lt_u32 s63, 13
	s_cbranch_scc1 .Lprep_m2ok
	s_cmp_lt_u32 s63, 16
	s_cbranch_scc1 .Lprep_zero
	s_sub_u32 s61, s61, 96
.Lprep_m2ok:
	v_readlane_b32 s56, v249, 14
	v_readlane_b32 s57, v249, 15
	s_mov_b64 s[66:67], 0
	s_nop 4
	s_movk_i32 s60, 0x4680
	s_branch .Lprep_tile
.Lprep_j3:
	s_sub_u32 s54, s52, 5504
	s_lshr_b32 s63, s54, 8
	s_lshl_b32 s63, s63, 4
	s_and_b32 s74, s54, 15
	s_or_b32 s63, s63, s74
	s_bfe_u32 s73, s54, 0x40004
	s_lshl_b32 s62, s73, 6
	s_add_u32 s68, s92, 0x1580000
	s_addc_u32 s69, s93, 0
	s_movk_i32 s70, 0x800
	s_mov_b32 s71, s62
	s_lshl_b32 s61, s63, 5
	s_add_u32 s61, s61, 2464
	v_readlane_b32 s56, v249, 14
	v_readlane_b32 s57, v249, 15
	s_mov_b64 s[66:67], 0
	s_nop 4
	s_movk_i32 s60, 0x4680
	s_branch .Lprep_tile
.Lprep_j4:
	s_sub_u32 s54, s52, 6528
	s_lshr_b32 s63, s54, 2
	s_and_b32 s73, s54, 3
	s_lshl_b32 s62, s73, 6
	s_add_u32 s68, s92, 0x1980000
	s_addc_u32 s69, s93, 0
	s_movk_i32 s70, 0x300
	s_mov_b32 s71, s62
	s_lshl_b32 s61, s63, 5
	v_readlane_b32 s56, v249, 20
	v_readlane_b32 s57, v249, 21
	v_readlane_b32 s66, v249, 16
	v_readlane_b32 s67, v249, 17
	s_nop 4
	s_movk_i32 s60, 0xc00
	s_branch .Lprep_tile
.Lprep_j5:
	s_sub_u32 s54, s52, 6624
	s_lshr_b32 s63, s54, 1
	s_and_b32 s73, s54, 1
	s_lshl_b32 s62, s73, 6
	s_add_u32 s68, s92, 0x1980000
	s_addc_u32 s69, s93, 0
	s_movk_i32 s70, 0x300
	s_add_u32 s71, s62, 256
	s_branch .Lprep_zero
.Lprep_j6:
	s_sub_u32 s54, s52, 6672
	s_and_b32 s63, s54, 31
	s_lshr_b32 s73, s54, 5
	s_lshl_b32 s62, s73, 6
	s_add_u32 s68, s92, 0x1a10000
	s_addc_u32 s69, s93, 0
	s_movk_i32 s70, 0x300
	s_add_u32 s71, s62, 256
	s_and_b32 s74, s63, 15
	s_lshr_b32 s61, s74, 1
	s_lshl_b32 s61, s61, 7
	s_and_b32 s74, s74, 1
	s_lshl_b32 s74, s74, 5
	s_add_u32 s61, s61, s74
	s_lshr_b32 s74, s63, 4
	s_lshl_b32 s74, s74, 6
	s_add_u32 s61, s61, s74
	v_readlane_b32 s56, v249, 22
	v_readlane_b32 s57, v249, 23
	v_readlane_b32 s66, v249, 18
	v_readlane_b32 s67, v249, 19
	s_nop 4
	s_movk_i32 s60, 0x1000
	s_branch .Lprep_tile
.Lprep_j7:
	s_sub_u32 s54, s52, 6736
	s_and_b32 s63, s54, 31
	s_lshr_b32 s73, s54, 5
	s_lshl_b32 s62, s73, 6
	s_add_u32 s68, s92, 0x1a10000
	s_addc_u32 s69, s93, 0
	s_movk_i32 s70, 0x300
	s_mov_b32 s71, s62
	s_branch .Lprep_zero
.Lprep_j8:
	s_sub_u32 s54, s52, 6864
	s_and_b32 s63, s54, 31
	s_lshr_b32 s73, s54, 5
	s_lshl_b32 s62, s73, 6
	s_add_u32 s68, s92, 0x1b00000
	s_addc_u32 s69, s93, 0
	s_movk_i32 s70, 0x400
	s_mov_b32 s71, s62
	s_lshl_b32 s61, s63, 5
	v_readlane_b32 s56, v249, 24
	v_readlane_b32 s57, v249, 25
	s_mov_b64 s[66:67], 0
	s_nop 4
	s_movk_i32 s60, 0x1000
	s_branch .Lprep_tile
.Lprep_j9:
	s_sub_u32 s54, s52, 7120
	s_lshr_b32 s63, s54, 8
	s_lshl_b32 s63, s63, 4
	s_and_b32 s74, s54, 15
	s_or_b32 s63, s63, s74
	s_bfe_u32 s73, s54, 0x40004
	s_lshl_b32 s62, s73, 6
	s_add_u32 s68, s92, 0x1c00000
	s_addc_u32 s69, s93, 0
	s_movk_i32 s70, 0x800
	s_mov_b32 s71, s62
	s_lshl_b32 s61, s63, 5
	s_mov_b64 s[56:57], s[50:51]
	s_mov_b64 s[66:67], 0
	s_movk_i32 s60, 0x1000
	s_branch .Lprep_tile
.Lprep_j10:
	s_sub_u32 s54, s52, 7632
	s_lshr_b32 s63, s54, 8
	s_lshl_b32 s63, s63, 4
	s_and_b32 s74, s54, 15
	s_or_b32 s63, s63, s74
	s_bfe_u32 s73, s54, 0x40004
	s_lshl_b32 s62, s73, 6
	s_add_u32 s68, s92, 0x1e00000
	s_addc_u32 s69, s93, 0
	s_movk_i32 s70, 0x800
	s_mov_b32 s71, s62
	s_lshl_b32 s61, s63, 5
	v_readlane_b32 s56, v249, 0
	v_readlane_b32 s57, v249, 1
	s_mov_b64 s[66:67], 0
	s_nop 4
	s_movk_i32 s60, 0x1000
	s_branch .Lprep_tile
.Lprep_j11:
	s_sub_u32 s54, s52, 8144
	s_lshr_b32 s63, s54, 8
	s_lshl_b32 s63, s63, 4
	s_and_b32 s74, s54, 15
	s_or_b32 s63, s63, s74
	s_bfe_u32 s73, s54, 0x40004
	s_lshl_b32 s62, s73, 6
	s_add_u32 s68, s92, 0x2000000
	s_addc_u32 s69, s93, 0
	s_movk_i32 s70, 0x800
	s_mov_b32 s71, s62
	s_lshr_b32 s61, s63, 3
	s_lshl_b32 s61, s61, 7
	s_and_b32 s74, s63, 7
	s_lshl_b32 s74, s74, 5
	s_add_u32 s61, s61, s74
	s_and_b32 s74, s63, 4
	s_cmp_lg_u32 s74, 0
	s_cselect_b32 s74, 0xa80, 0
	s_add_u32 s61, s61, s74
	v_readlane_b32 s56, v249, 2
	v_readlane_b32 s57, v249, 3
	s_mov_b64 s[66:67], 0
	s_nop 4
	s_movk_i32 s60, 0x5800
	s_branch .Lprep_tile
.Lprep_j12:
	s_sub_u32 s54, s52, 10960
	s_and_b32 s63, s54, 31
	s_lshr_b32 s73, s54, 5
	s_lshl_b32 s62, s73, 6
	s_add_u32 s68, s92, 0x2b00000
	s_addc_u32 s69, s93, 0
	s_movk_i32 s70, 0x1600
	s_mov_b32 s71, s62
	s_lshl_b32 s61, s63, 5
	v_readlane_b32 s56, v249, 4
	v_readlane_b32 s57, v249, 5
	s_mov_b64 s[66:67], 0
	s_nop 4
	s_movk_i32 s60, 0x1000
	s_branch .Lprep_tile
.Lprep_j13:
	s_sub_u32 s54, s52, 12368
	s_lshr_b32 s72, s54, 3
	s_bfe_u32 s63, s54, 0x20001
	s_and_b32 s73, s54, 1
	s_lshl_b32 s62, s73, 6
	s_add_u32 s68, s92, 0x3080000
	s_addc_u32 s69, s93, 0
	s_mul_i32 s74, s72, 0x10000
	s_add_u32 s68, s68, s74
	s_addc_u32 s69, s69, 0
	s_movk_i32 s70, 0x100
	s_mov_b32 s71, s62
	s_lshl_b32 s61, s63, 5
	s_mov_b64 s[56:57], s[40:41]
	s_mov_b64 s[66:67], 0
	s_mul_i32 s74, s72, 0x10000
	s_add_u32 s56, s56, s74
	s_addc_u32 s57, s57, 0
	s_movk_i32 s60, 0x200
	s_branch .Lprep_tile
; #define LAS __attribute__((address_space(3)))
; __device__ __forceinline__ void tr_item(const TJob& jb, int item, LAS float* scr, int lane) {
;     const int nkb = jb.K >> 6, per_batch = jb.nrb * nkb;
;     const int bt = item / per_batch, r = item - bt * per_batch, rb = r / nkb, kb = r - rb * nkb;
;     const int sc = srccol(jb.map, rb), k0 = 64 * kb;
;     if (jb.src != nullptr && sc >= 0) {
;         const float* src = jb.src + (size_t)bt * jb.sbs;
; #pragma unroll 8
;         for (int i = 0; i < 32; ++i) { const int kk = 2 * i + (lane >> 5);
;             float v = src[(size_t)(k0 + kk) * jb.ldsrc + sc + (lane & 31)];
;             if (jb.scale) v *= jb.scale[k0 + kk];
;             scr[kk * 33 + (lane & 31)] = v; }
.Lprep_j14:
	s_sub_u32 s54, s52, 12496
	s_lshr_b32 s72, s54, 3
	s_bfe_u32 s63, s54, 0x20001
	s_and_b32 s73, s54, 1
	s_lshl_b32 s62, s73, 6
	s_add_u32 s68, s92, 0x3088000
	s_addc_u32 s69, s93, 0
	s_mul_i32 s74, s72, 0x10000
	s_add_u32 s68, s68, s74
	s_addc_u32 s69, s69, 0
	s_movk_i32 s70, 0x100
	s_mov_b32 s71, s62
	s_lshl_b32 s61, s63, 5
	s_mov_b64 s[56:57], s[44:45]
	s_mov_b64 s[66:67], 0
	s_mul_i32 s74, s72, 0x10000
	s_add_u32 s56, s56, s74
	s_addc_u32 s57, s57, 0
	s_movk_i32 s60, 0x200
	s_branch .Lprep_tile
.Lprep_tile:
	s_mul_i32 s74, s62, s60
	s_lshl_b32 s75, s61, 2
	s_add_u32 s74, s74, s75
	s_add_u32 s76, s56, s74
	s_addc_u32 s77, s57, 0
	s_lshl_b32 s75, s60, 3
	v_mad_u32_u24 v242, v240, s60, v241
	global_load_dwordx4 v[160:163], v242, s[76:77]
	s_add_u32 s76, s76, s75
	s_addc_u32 s77, s77, 0
	global_load_dwordx4 v[164:167], v242, s[76:77]
	s_add_u32 s76, s76, s75
	s_addc_u32 s77, s77, 0
	global_load_dwordx4 v[168:171], v242, s[76:77]
	s_add_u32 s76, s76, s75
	s_addc_u32 s77, s77, 0
	global_load_dwordx4 v[172:175], v242, s[76:77]
	s_add_u32 s76, s76, s75
	s_addc_u32 s77, s77, 0
	global_load_dwordx4 v[176:179], v242, s[76:77]
	s_add_u32 s76, s76, s75
	s_addc_u32 s77, s77, 0
	global_load_dwordx4 v[180:183], v242, s[76:77]
	s_add_u32 s76, s76, s75
	s_addc_u32 s77, s77, 0
	global_load_dwordx4 v[184:187], v242, s[76:77]
	s_add_u32 s76, s76, s75
	s_addc_u32 s77, s77, 0
	global_load_dwordx4 v[188:191], v242, s[76:77]
	s_cmp_eq_u64 s[66:67], 0
	s_cbranch_scc1 .Lprep_noscale
	s_lshl_b32 s74, s62, 2
	s_add_u32 s78, s66, s74
	s_addc_u32 s79, s67, 0
	global_load_dword v232, v246, s[78:79] offset:0
	global_load_dword v233, v246, s[78:79] offset:32
	global_load_dword v234, v246, s[78:79] offset:64
	global_load_dword v235, v246, s[78:79] offset:96
	global_load_dword v236, v246, s[78:79] offset:128
	global_load_dword v237, v246, s[78:79] offset:160
	global_load_dword v238, v246, s[78:79] offset:192
	global_load_dword v239, v246, s[78:79] offset:224
	s_waitcnt vmcnt(0)
	v_mul_f32_e32 v160, v160, v232
	v_mul_f32_e32 v161, v161, v232
	v_mul_f32_e32 v162, v162, v232
	v_mul_f32_e32 v163, v163, v232
	v_mul_f32_e32 v164, v164, v233
	v_mul_f32_e32 v165, v165, v233
	v_mul_f32_e32 v166, v166, v233
	v_mul_f32_e32 v167, v167, v233
	v_mul_f32_e32 v168, v168, v234
	v_mul_f32_e32 v169, v169, v234
	v_mul_f32_e32 v170, v170, v234
	v_mul_f32_e32 v171, v171, v234
	v_mul_f32_e32 v172, v172, v235
	v_mul_f32_e32 v173, v173, v235
	v_mul_f32_e32 v174, v174, v235
	v_mul_f32_e32 v175, v175, v235
	v_mul_f32_e32 v176, v176, v236
	v_mul_f32_e32 v177, v177, v236
	v_mul_f32_e32 v178, v178, v236
	v_mul_f32_e32 v179, v179, v236
	v_mul_f32_e32 v180, v180, v237
	v_mul_f32_e32 v181, v181, v237
	v_mul_f32_e32 v182, v182, v237
	v_mul_f32_e32 v183, v183, v237
	v_mul_f32_e32 v184, v184, v238
	v_mul_f32_e32 v185, v185, v238
	v_mul_f32_e32 v186, v186, v238
	v_mul_f32_e32 v187, v187, v238
	v_mul_f32_e32 v188, v188, v239
	v_mul_f32_e32 v189, v189, v239
	v_mul_f32_e32 v190, v190, v239
	v_mul_f32_e32 v191, v191, v239
; #define LAS __attribute__((address_space(3)))
; __device__ __forceinline__ unsigned pk_bf16(float lo, float hi) { const f32x2 v = {lo, hi}; const bf16x2_t b = __builtin_convertvector(v, bf16x2_t); return __builtin_bit_cast(unsigned, b); }
; __device__ __forceinline__ void tr_item(const TJob& jb, int item, LAS float* scr, int lane) {
;     ...
;             scr[kk * 33 + (lane & 31)] = v; }
;     } else {
; #pragma unroll 8
;         for (int i = 0; i < 32; ++i) { const int kk = 2 * i + (lane >> 5); scr[kk * 33 + (lane & 31)] = 0.f; }
;     }
;     asm volatile("s_waitcnt lgkmcnt(0)" ::: "memory");
;     bf16_t* dst = jb.dst + (size_t)bt * jb.dbs;
;     const int c = lane & 7;
; #pragma unroll
;     for (int j = 0; j < 4; ++j) { const int n = (lane >> 3) + 8 * j; const LAS float* s = scr + (8 * c) * 33 + n;
;         u32x4 o; o.x = pk_bf16(s[0 * 33], s[1 * 33]); o.y = pk_bf16(s[2 * 33], s[3 * 33]); o.z = pk_bf16(s[4 * 33], s[5 * 33]); o.w = pk_bf16(s[6 * 33], s[7 * 33]);
;         *(u32x4*)(dst + (size_t)(32 * rb + n) * jb.lddst + jb.dstk0 + k0 + 8 * c) = o; }
;     asm volatile("s_waitcnt lgkmcnt(0)" ::: "memory");
; }
; __device__ __forceinline__ void phase_prep(const Params& p, LAS unsigned char* lds) {
;     ...
;             for (int i = first; i < n; i += NGW) tr_item(jb, i, scr, lane);
;             base += n;
.Lprep_noscale:
	s_waitcnt vmcnt(7)
	ds_write_b32 v244, v160 offset:0
	ds_write_b32 v244, v161 offset:4
	ds_write_b32 v244, v162 offset:8
	ds_write_b32 v244, v163 offset:12
	s_waitcnt vmcnt(6)
	ds_write_b32 v244, v164 offset:1056
	ds_write_b32 v244, v165 offset:1060
	ds_write_b32 v244, v166 offset:1064
	ds_write_b32 v244, v167 offset:1068
	s_waitcnt vmcnt(5)
	ds_write_b32 v244, v168 offset:2112
	ds_write_b32 v244, v169 offset:2116
	ds_write_b32 v244, v170 offset:2120
	ds_write_b32 v244, v171 offset:2124
	s_waitcnt vmcnt(4)
	ds_write_b32 v244, v172 offset:3168
	ds_write_b32 v244, v173 offset:3172
	ds_write_b32 v244, v174 offset:3176
	ds_write_b32 v244, v175 offset:3180
	s_waitcnt vmcnt(3)
	ds_write_b32 v244, v176 offset:4224
	ds_write_b32 v244, v177 offset:4228
	ds_write_b32 v244, v178 offset:4232
	ds_write_b32 v244, v179 offset:4236
	s_waitcnt vmcnt(2)
	ds_write_b32 v244, v180 offset:5280
	ds_write_b32 v244, v181 offset:5284
	ds_write_b32 v244, v182 offset:5288
	ds_write_b32 v244, v183 offset:5292
	s_waitcnt vmcnt(1)
	ds_write_b32 v244, v184 offset:6336
	ds_write_b32 v244, v185 offset:6340
	ds_write_b32 v244, v186 offset:6344
	ds_write_b32 v244, v187 offset:6348
	s_waitcnt vmcnt(0)
	ds_write_b32 v244, v188 offset:7392
	ds_write_b32 v244, v189 offset:7396
	ds_write_b32 v244, v190 offset:7400
	ds_write_b32 v244, v191 offset:7404
	s_waitcnt lgkmcnt(0)
	ds_read_b32 v192, v245 offset:0
	ds_read_b32 v193, v245 offset:132
	ds_read_b32 v194, v245 offset:264
	ds_read_b32 v195, v245 offset:396
	ds_read_b32 v196, v245 offset:528
	ds_read_b32 v197, v245 offset:660
	ds_read_b32 v198, v245 offset:792
	ds_read_b32 v199, v245 offset:924
	ds_read_b32 v200, v245 offset:32
	ds_read_b32 v201, v245 offset:164
	ds_read_b32 v202, v245 offset:296
	ds_read_b32 v203, v245 offset:428
	ds_read_b32 v204, v245 offset:560
	ds_read_b32 v205, v245 offset:692
	ds_read_b32 v206, v245 offset:824
	ds_read_b32 v207, v245 offset:956
	ds_read_b32 v208, v245 offset:64
	ds_read_b32 v209, v245 offset:196
	ds_read_b32 v210, v245 offset:328
	ds_read_b32 v211, v245 offset:460
	ds_read_b32 v212, v245 offset:592
	ds_read_b32 v213, v245 offset:724
	ds_read_b32 v214, v245 offset:856
	ds_read_b32 v215, v245 offset:988
	ds_read_b32 v216, v245 offset:96
	ds_read_b32 v217, v245 offset:228
	ds_read_b32 v218, v245 offset:360
	ds_read_b32 v219, v245 offset:492
	ds_read_b32 v220, v245 offset:624
	ds_read_b32 v221, v245 offset:756
	ds_read_b32 v222, v245 offset:888
	ds_read_b32 v223, v245 offset:1020
	s_lshl_b32 s74, s63, 5
	s_mul_i32 s74, s74, s70
	s_lshl_b32 s75, s71, 1
	s_add_u32 s74, s74, s75
	s_add_u32 s76, s68, s74
	s_addc_u32 s77, s69, 0
	s_lshl_b32 s75, s70, 3
	v_mad_u32_u24 v243, v240, s70, v241
	s_waitcnt lgkmcnt(0)
	v_cvt_pk_bf16_f32 v224, v192, v193
	v_cvt_pk_bf16_f32 v225, v194, v195
	v_cvt_pk_bf16_f32 v226, v196, v197
	v_cvt_pk_bf16_f32 v227, v198, v199
	global_store_dwordx4 v243, v[224:227], s[76:77]
	s_add_u32 s76, s76, s75
	s_addc_u32 s77, s77, 0
	v_cvt_pk_bf16_f32 v228, v200, v201
	v_cvt_pk_bf16_f32 v229, v202, v203
	v_cvt_pk_bf16_f32 v230, v204, v205
	v_cvt_pk_bf16_f32 v231, v206, v207
	global_store_dwordx4 v243, v[228:231], s[76:77]
	s_add_u32 s76, s76, s75
	s_addc_u32 s77, s77, 0
	v_cvt_pk_bf16_f32 v232, v208, v209
	v_cvt_pk_bf16_f32 v233, v210, v211
	v_cvt_pk_bf16_f32 v234, v212, v213
	v_cvt_pk_bf16_f32 v235, v214, v215
	global_store_dwordx4 v243, v[232:235], s[76:77]
	s_add_u32 s76, s76, s75
	s_addc_u32 s77, s77, 0
	v_cvt_pk_bf16_f32 v236, v216, v217
	v_cvt_pk_bf16_f32 v237, v218, v219
	v_cvt_pk_bf16_f32 v238, v220, v221
	v_cvt_pk_bf16_f32 v239, v222, v223
	global_store_dwordx4 v243, v[236:239], s[76:77]
	s_branch .Lprep_next
.Lprep_zero:
	s_lshl_b32 s74, s63, 5
	s_mul_i32 s74, s74, s70
	s_lshl_b32 s75, s71, 1
	s_add_u32 s74, s74, s75
	s_add_u32 s76, s68, s74
	s_addc_u32 s77, s69, 0
	s_lshl_b32 s75, s70, 3
	v_mad_u32_u24 v243, v240, s70, v241
	v_mov_b32_e32 v224, 0
	v_mov_b32_e32 v225, 0
	v_mov_b32_e32 v226, 0
	v_mov_b32_e32 v227, 0
	global_store_dwordx4 v243, v[224:227], s[76:77]
	s_add_u32 s76, s76, s75
	s_addc_u32 s77, s77, 0
	global_store_dwordx4 v243, v[224:227], s[76:77]
	s_add_u32 s76, s76, s75
	s_addc_u32 s77, s77, 0
	global_store_dwordx4 v243, v[224:227], s[76:77]
	s_add_u32 s76, s76, s75
	s_addc_u32 s77, s77, 0
	global_store_dwordx4 v243, v[224:227], s[76:77]
.Lprep_next:
	s_add_u32 s52, s52, s53
	s_branch .Lprep_item
.Lprep_done:
.LBB0_131:
	v_lshl_add_u32 v0, s2, 9, v128
	s_mov_b32 s0, 0x10000
	v_cmp_gt_i32_e32 vcc, s0, v0
	s_and_saveexec_b64 s[0:1], vcc
	v_readlane_b32 s92, v249, 54
	v_readlane_b32 s90, v249, 58
	v_readlane_b32 s96, v249, 30
	v_readlane_b32 s64, v249, 28
	v_readlane_b32 s30, v249, 26
	v_readlane_b32 s93, v249, 55
	v_readlane_b32 s94, v249, 56
	v_readlane_b32 s95, v249, 57
	v_readlane_b32 s91, v249, 59
	v_readlane_b32 s97, v249, 31
	v_readlane_b32 s65, v249, 29
	v_readlane_b32 s31, v249, 27
	s_cbranch_execz .LBB0_137
	v_and_b32_e32 v1, 15, v128
	v_cmp_ne_u32_e32 vcc, 0, v1
	v_mov_b32_e32 v2, 1.0
	s_and_saveexec_b64 s[4:5], vcc
	s_cbranch_execz .LBB0_136
	s_mov_b32 s24, 0x3c1c381e
	s_mov_b64 s[6:7], 0
	v_mov_b64_e32 v[2:3], 1.0
	s_mov_b32 s25, 0x3fe1feb3
